# P2 work deal: light workgroups with three up-projection units take 4 GLA chunk-update items, those with two units take 6 (was 5 and 5); same items, same order within a workgroup
# baseline (speedup 1.0000x reference)
; #define LAS __attribute__((address_space(3)))
; #define FRESH() const int lane = fresh_lane(); int wave = wave_s; asm volatile("" : "+s"(wave)); const int tid = wave * 64 + lane; (void)tid; unsigned char* ws = p.ws; asm volatile("" : "+s"(ws)); (void)ws; Params pl = p; pl.ws = ws; (void)pl
; __global__ void __launch_bounds__(512, 2) hymba_fwd(Params p) {
;     extern __shared__ __attribute__((aligned(16))) unsigned char lds_raw[];
;     LAS unsigned char* lds = (LAS unsigned char*)lds_raw;
;     cg::grid_group grid = cg::this_grid();
;     if (threadIdx.x < 2) ((volatile LAS unsigned*)(lds + LDS_BYTES - 64))[threadIdx.x] = 0u;
;     __syncthreads();
;     (void)xcd_barrier_post((unsigned*)p.ws, (volatile LAS unsigned*)(lds + LDS_BYTES - 64));
;     const int wave_s = __builtin_amdgcn_readfirstlane(threadIdx.x >> 6);
;     const int G = gridDim.x, bx = blockIdx.x;
;     const int vcu = (G % 8 == 0) ? (bx % 8) * (G / 8) + bx / 8 : bx;
;     ...
;         const bool bal = (G == 256);
;         const bool heavy = bal && !(vcu & 1);
;         const int hv = vcu >> 1;
;     ...
;         { FRESH();
;             pg8::Gemm g{(const bf16_t*)(ws + WS_CQ), (const bf16_t*)(ws + WS_WUP) + (size_t)l * WUP_ROWS * 256, 2 * T, WUP_ROWS, 256};
;             pg8::StaticOrder S;
;             if (!bal) S.init_up(vcu, G, 448); else if (heavy) S.init_up(hv, 448, 448); else S.init_up(128 + hv, 128, 448);
;             EpiUp E{(bf16_t*)(ws + WS_QR), (bf16_t*)(ws + WS_KVR)};
;             pg8::gemm_phase<EpiUp>(lds, g, S, E, tid);
;         }
;         __syncthreads();
;     ...
;         { FRESH();
;             int first, step, lim;
;             if (!bal) { first = vcu; step = G; lim = 1024; } else if (heavy) { first = 640 + hv * 3; step = 1; lim = first + 3; } else { first = hv * 5; step = 1; lim = first + 5; }
;             gla_pass<false>(p, l, lds, tid, lane, wave, first, step, lim); }
.LBB0_188:
	s_ashr_i32 s1, s89, 1
	s_lshl_b32 s3, s1, 2
	s_mul_i32 s5, s1, 3
	s_and_b32 s0, s89, 1
	s_mul_i32 s4, s1, 6
	s_addk_i32 s4, 0xff80
	s_cmp_lt_i32 s1, 64
	s_cselect_b32 s3, s3, s4
	s_cselect_b32 s4, 4, 6
	s_add_i32 s4, s3, s4
	s_add_i32 s6, s5, 0x280
	s_addk_i32 s5, 0x283
	s_cmp_eq_u32 s0, 0
	v_writelane_b32 v254, s36, 20
	s_cselect_b32 s3, s6, s3
	s_cmpk_eq_i32 s68, 0x100
	v_writelane_b32 v254, s37, 21
	s_cselect_b32 s6, 1, s68
	v_writelane_b32 v254, s6, 22
	s_cmp_eq_u32 s0, 0
	s_movk_i32 s6, 0x1c0
	s_cselect_b32 s6, s6, 0x80
	s_cselect_b32 s4, s5, s4
	s_add_i32 s5, s1, 0x200
	s_cmp_eq_u32 s0, 0
	s_cselect_b32 s5, s5, 0x280
	s_cmpk_eq_i32 s68, 0x100
	s_cselect_b32 s19, s4, 0x400
	s_cselect_b32 s20, s3, s89
	s_xor_b32 s3, s0, 1
	s_cmpk_eq_i32 s68, 0x100
	s_cselect_b32 s3, s3, 0
	v_writelane_b32 v254, s3, 23
	s_add_i32 s3, s89, 0x200
	s_cmpk_eq_i32 s68, 0x100
	s_cselect_b32 s4, 0x280, s68
	s_cselect_b32 s3, s5, s3
	s_lshl_b32 s0, s0, 7
	s_add_i32 s0, s0, s1
	v_writelane_b32 v254, s4, 24
	s_cmpk_eq_i32 s68, 0x100
	v_writelane_b32 v254, s3, 25
	s_cselect_b32 s21, s6, s68
	s_cselect_b32 s3, s0, s89
	s_cmpk_lg_i32 s68, 0x100
	s_cselect_b64 s[0:1], -1, 0
	s_cmpk_lt_i32 s89, 0x80
	s_cselect_b64 s[4:5], -1, 0
	s_sub_i32 s10, s68, s89
	s_add_i32 s6, s10, 0x7f
	s_add_u32 s7, s50, 0x8000
	v_writelane_b32 v254, s7, 26
	s_addc_u32 s7, s51, 0
	s_add_u32 s38, s50, 0x200
	s_addc_u32 s39, s51, 0
	s_add_u32 s40, s50, 0x1000
	s_addc_u32 s41, s51, 0
	s_add_u32 s42, s50, 0x1100
	s_addc_u32 s43, s51, 0
	s_add_u32 s44, s50, 0x1200
	s_addc_u32 s45, s51, 0
	s_add_u32 s46, s50, 0x1300
	s_addc_u32 s47, s51, 0
	s_add_u32 s12, s50, 0x3400
	v_writelane_b32 v254, s7, 27
	s_addc_u32 s13, s51, 0
	v_writelane_b32 v254, s12, 28
	s_mov_b32 s93, 0
	s_mul_i32 s69, s69, s68
	v_writelane_b32 v254, s13, 29
	s_add_u32 s12, s50, 0x3500
	s_addc_u32 s13, s51, 0
	v_writelane_b32 v254, s12, 30
	s_cmpk_lt_i32 s3, 0x1c0
	s_mul_i32 s69, s69, s2
	v_writelane_b32 v254, s13, 31
	s_cselect_b64 s[12:13], -1, 0
	s_and_b32 s11, s3, 0xff
	v_writelane_b32 v254, s12, 32
	s_mulk_i32 s11, 0xab
	s_add_i32 s7, s3, 0xffffff00
	v_writelane_b32 v254, s13, 33
	s_lshr_b32 s12, s11, 9
	s_mul_i32 s11, s12, -3
	s_add_i32 s13, s7, s11
	s_ashr_i32 s11, s3, 2
	s_add_i32 s14, s11, 64
	s_and_b32 s11, s3, 3
	s_add_i32 s15, s11, 3
	s_ashr_i32 s22, s21, 31
	s_ashr_i32 s11, s3, 31
	s_add_u32 s60, s50, 0x4600000
	s_addc_u32 s61, s51, 0
	s_add_u32 s16, s50, 0x8e00180
	s_addc_u32 s17, s51, 0
	v_writelane_b32 v254, s16, 34
	v_mov_b32_e32 v1, 0
	v_mov_b32_e32 v228, 0x358637bd
	v_writelane_b32 v254, s17, 35
	s_add_u32 s16, s50, 0x20000
	s_addc_u32 s17, s51, 0
	v_writelane_b32 v254, s16, 36
	v_mov_b32_e32 v229, 0xff800000
	s_movk_i32 s80, 0x2000
	v_writelane_b32 v254, s17, 37
	s_add_u32 s16, s50, 0x30000
	s_addc_u32 s17, s51, 0
	s_add_u32 s24, s50, 0xf700000
	s_addc_u32 s25, s51, 0
	s_add_u32 s26, s50, 0x2600000
	v_writelane_b32 v254, s16, 38
	s_addc_u32 s27, s51, 0
	s_movk_i32 s81, 0x4000
	v_writelane_b32 v254, s17, 39
	s_add_u32 s16, s50, 0xf600000
	s_addc_u32 s17, s51, 0
	v_writelane_b32 v254, s16, 40
	s_cmpk_lt_i32 s91, 0x100
	s_mov_b32 s95, 0x800000
	v_writelane_b32 v254, s17, 41
	s_cselect_b64 s[16:17], -1, 0
	v_writelane_b32 v254, s16, 42
	s_movk_i32 s76, 0x600
	s_movk_i32 s77, 0x190
	v_writelane_b32 v254, s17, 43
	s_mov_b32 s65, 0xc800
	v_readlane_b32 s16, v254, 19
	s_cmp_lt_i32 s16, 0x20000
	s_cselect_b64 s[16:17], -1, 0
	v_writelane_b32 v254, s16, 44
	s_cmpk_lt_i32 s89, 0x100
	s_mov_b32 s58, 0xff800000
	v_writelane_b32 v254, s17, 45
	s_cselect_b64 s[16:17], -1, 0
	v_writelane_b32 v254, s16, 46
	s_mov_b64 s[84:85], 0x80
	s_mov_b32 s88, 0x3a800000
	v_writelane_b32 v254, s17, 47
	s_add_u32 s16, s50, 0x9600000
	s_addc_u32 s17, s51, 0
	v_writelane_b32 v254, s16, 48
	s_mov_b32 s90, 0x358637bd
	s_mov_b64 s[70:71], 0x18000
	v_writelane_b32 v254, s17, 49
	s_add_u32 s16, s50, 0xe600000
	v_writelane_b32 v254, s16, 50
	s_addc_u32 s16, s51, 0
	v_writelane_b32 v254, s16, 51
	s_add_u32 s16, s50, 0xce00000
	v_writelane_b32 v254, s16, 52
	s_addc_u32 s16, s51, 0
	s_cmpk_lt_i32 s91, 0x400
	v_writelane_b32 v254, s16, 53
	s_cselect_b64 s[16:17], -1, 0
	v_writelane_b32 v254, s16, 54
	s_mov_b32 s86, s93
	s_nop 0
	v_writelane_b32 v254, s17, 55
	s_lshl_b32 s16, s91, 4
	s_and_b32 s16, s16, 0x3fc0
	v_writelane_b32 v254, s16, 56
	s_and_b32 s16, s91, 0x3ff
	s_and_b32 s17, s91, 3
	s_lshl_b32 s18, s16, 13
	s_add_u32 s28, s24, s18
	v_writelane_b32 v254, s24, 57
	s_addc_u32 s29, s25, 0
	s_lshl_b32 s18, s17, 7
	v_writelane_b32 v254, s25, 58
	v_writelane_b32 v254, s28, 59
; #define FRESH() const int lane = fresh_lane(); int wave = wave_s; asm volatile("" : "+s"(wave)); const int tid = wave * 64 + lane; (void)tid; unsigned char* ws = p.ws; asm volatile("" : "+s"(ws)); (void)ws; Params pl = p; pl.ws = ws; (void)pl
; __global__ void __launch_bounds__(512, 2) hymba_fwd(Params p) {
;     ...
;     const int wave_s = __builtin_amdgcn_readfirstlane(threadIdx.x >> 6);
;     const int G = gridDim.x, bx = blockIdx.x;
;     const int vcu = (G % 8 == 0) ? (bx % 8) * (G / 8) + bx / 8 : bx;
;     ...
;     for (int rep = 0; rep < ((DUPMASK & 1) ? 2 : 1); ++rep) { FRESH(); p0_prologue(pl, lds, tid, lane, wave); __syncthreads(); }
;     ...
;     xcd_barrier((unsigned*)p.ws, lds);
;     if (gridDim.x == 0x7fffffffu) grid.sync();
;     for (int l = 0; l < DEPTH; ++l) {
;         for (int ph = 0; ph < 2; ++ph) {
;     ...
;             { FRESH(); float* SSQ = (float*)(ws + WS_SSQ);
;                 pg8::Gemm g{(const bf16_t*)(ws + WS_XB), (const bf16_t*)(ws + WS_WIN) + (size_t)l * N1 * DM, T, N1, DM};
;                 pg8::StaticOrder S; if (ph == 0) S.init_in(vcu, G, 512); else if (G == 256) S.init_in((vcu & 1) ? 640 : 512 + (vcu >> 1), 640, 640); else S.init_in(512 + vcu, G, 640);
;                 EpiZ E{(bf16_t*)(ws + WS_Z), (bf16_t*)(ws + WS_CQ), (bf16_t*)(ws + WS_MISC), SSQ};
;                 pg8::gemm_phase<EpiZ, true, (DUPMASK & 4096) != 0>(lds, g, S, E, tid);
;                 __syncthreads();
;                 if (ph == 1) {
;                     const int nmine = (G == 256) ? ((vcu & 1) ? 0 : 1) : ((vcu < 128) ? (128 - vcu + G - 1) / G : 0);
;                     if (nmine > 0 && threadIdx.x == 0) __hip_atomic_fetch_add((unsigned*)p.ws + CW_LATE + 64 * l, (unsigned)nmine, __ATOMIC_RELAXED, __HIP_MEMORY_SCOPE_AGENT);
	s_add_u32 s24, s60, s18
	s_addc_u32 s25, s61, 0
	v_writelane_b32 v254, s29, 60
	v_writelane_b32 v254, s24, 61
	s_lshl_b32 s16, s16, 15
	s_nop 0
	v_writelane_b32 v254, s25, 62
	s_add_u32 s24, s26, s16
	v_writelane_b32 v254, s26, 63
	s_addc_u32 s25, s27, 0
	s_nop 0
	v_writelane_b32 v255, s27, 0
	v_writelane_b32 v255, s24, 1
	s_nop 1
	v_writelane_b32 v255, s25, 2
	s_add_u32 s24, s50, 0xae00000
	s_addc_u32 s25, s51, 0
	v_writelane_b32 v255, s24, 3
	s_and_b64 s[0:1], s[0:1], s[4:5]
	s_nop 0
	v_writelane_b32 v255, s25, 4
	v_writelane_b32 v255, s0, 5
	s_nop 1
	v_writelane_b32 v255, s1, 6
	s_ashr_i32 s0, s91, 31
	v_writelane_b32 v255, s0, 7
	s_lshr_b32 s0, s0, 29
	s_add_i32 s0, s91, s0
	s_ashr_i32 s1, s0, 3
	s_and_b32 s0, s0, -8
	s_sub_i32 s0, s91, s0
	s_lshl_b32 s4, s0, 5
	s_cmpk_lt_i32 s3, 0x100
	s_cselect_b32 s14, s14, s12
	s_mov_b32 s12, s14
	s_cselect_b32 s24, s15, s13
	s_ashr_i32 s15, s14, 31
	v_writelane_b32 v255, s12, 8
	s_ashr_i32 s25, s24, 31
	s_nop 0
	v_writelane_b32 v255, s13, 9
	s_lshl_b64 s[12:13], s[14:15], 17
	v_writelane_b32 v255, s12, 10
	s_nop 1
	v_writelane_b32 v255, s13, 11
	s_mov_b32 s12, s24
	v_writelane_b32 v255, s12, 12
	s_nop 1
	v_writelane_b32 v255, s13, 13
	s_lshl_b64 s[12:13], s[24:25], 17
	v_writelane_b32 v255, s12, 14
	s_cmp_lt_i32 s20, s19
	s_nop 0
	v_writelane_b32 v255, s13, 15
	v_writelane_b32 v255, s19, 16
	s_cselect_b64 s[12:13], -1, 0
	v_writelane_b32 v255, s12, 17
	s_lshl_b32 s5, s20, 4
	s_and_b32 s5, s5, 0x3fc0
	v_writelane_b32 v255, s13, 18
	v_writelane_b32 v255, s5, 19
	s_and_b32 s5, s20, 3
	s_lshl_b32 s12, s5, 7
	s_lshl_b32 s16, s5, 6
	s_add_u32 s12, s60, s12
	s_addc_u32 s13, s61, 0
	s_cmp_lt_i32 s0, 0
	s_mul_i32 s0, s0, 33
	s_cselect_b32 s0, s0, s4
	s_add_i32 s0, s0, s1
	s_ashr_i32 s1, s0, 31
	s_lshr_b32 s1, s1, 27
	s_add_i32 s1, s0, s1
	s_and_b32 s4, s1, 0xffe0
	s_sub_i32 s0, s0, s4
	s_bfe_i32 s4, s0, 0x80000
	v_writelane_b32 v255, s20, 20
	s_bfe_u32 s4, s4, 0x3000c
	v_writelane_b32 v255, s12, 21
	s_add_i32 s4, s0, s4
	s_sub_i32 s10, 0xffffff81, s10
	v_writelane_b32 v255, s13, 22
	s_and_b32 s12, s4, 0xf8
	s_sub_i32 s0, s0, s12
	s_abs_i32 s12, s68
	v_cvt_f32_u32_e32 v0, s12
	s_sub_i32 s13, 0, s12
	s_max_i32 s10, s6, s10
	s_ashr_i32 s1, s1, 5
	v_rcp_iflag_f32_e32 v0, v0
	s_bfe_i32 s4, s4, 0x80000
	s_lshl_b32 s1, s1, 3
	s_sext_i32_i16 s4, s4
	v_mul_f32_e32 v0, 0x4f7ffffe, v0
	v_cvt_u32_f32_e32 v0, v0
	s_sext_i32_i8 s0, s0
	v_readfirstlane_b32 s14, v0
	s_mul_i32 s13, s13, s14
	s_mul_hi_u32 s13, s14, s13
	s_add_i32 s14, s14, s13
	s_mul_hi_u32 s13, s10, s14
	s_mul_i32 s14, s13, s12
	s_sub_i32 s10, s10, s14
	s_add_i32 s14, s1, s0
	s_ashr_i32 s0, s4, 3
	v_writelane_b32 v255, s0, 23
	s_lshr_b32 s0, s4, 3
	s_bfe_i64 s[0:1], s[0:1], 0x100000
	s_lshl_b64 s[0:1], s[0:1], 19
	v_writelane_b32 v255, s0, 24
	s_ashr_i32 s15, s14, 31
	s_sub_i32 s4, s10, s12
	v_writelane_b32 v255, s1, 25
	s_xor_b32 s0, s6, s68
	s_ashr_i32 s0, s0, 31
	s_add_i32 s1, s13, 1
	s_mov_b32 s6, s14
	s_lshl_b64 s[14:15], s[14:15], 19
	s_cmp_ge_u32 s10, s12
	v_writelane_b32 v255, s6, 26
	s_cselect_b32 s1, s1, s13
	s_cselect_b32 s4, s4, s10
	v_writelane_b32 v255, s7, 27
	s_add_i32 s6, s1, 1
	s_cmp_ge_u32 s4, s12
	s_cselect_b32 s1, s6, s1
	v_writelane_b32 v255, s14, 28
	s_xor_b32 s1, s1, s0
	s_sub_i32 s0, s1, s0
	v_writelane_b32 v255, s15, 29
	v_writelane_b32 v255, s0, 30
	s_lshl_b32 s0, s5, 8
	s_add_u32 s0, s60, s0
	s_addc_u32 s1, s61, 0
	v_writelane_b32 v255, s0, 31
	s_nop 1
	v_writelane_b32 v255, s1, 32
	s_lshl_b32 s0, s17, 8
	s_add_u32 s0, s60, s0
	s_addc_u32 s1, s61, 0
	v_writelane_b32 v255, s0, 33
	s_mov_b32 s17, s93
	s_nop 0
	v_writelane_b32 v255, s1, 34
	s_add_i32 s0, s7, s21
	v_writelane_b32 v255, s0, 35
	v_writelane_b32 v255, s21, 36
	s_add_u32 s0, s21, s3
	v_writelane_b32 v255, s22, 37
	s_addc_u32 s1, s22, s11
	v_writelane_b32 v255, s0, 38
	s_lshl_b32 s37, s68, 6
	s_nop 0
	v_writelane_b32 v255, s1, 39
	v_writelane_b32 v255, s16, 40
	s_xor_b64 s[0:1], s[8:9], -1
	s_nop 0
	v_writelane_b32 v255, s17, 41
	v_writelane_b32 v255, s0, 42
	s_nop 1
	v_writelane_b32 v255, s1, 43
	s_lshl_b32 s0, s91, 6
	v_writelane_b32 v255, s0, 44
	s_add_i32 s0, 0, 0x23fc0
	v_writelane_b32 v255, s0, 45
	s_add_i32 s0, 0, 0x23fc4
	v_writelane_b32 v255, s0, 46
	s_add_i32 s0, 0, 0x11800
	v_writelane_b32 v255, s0, 47
	s_add_i32 s0, 0, 0x12800
	v_writelane_b32 v255, s0, 48
	s_add_i32 s0, 0, 0x13800
	v_writelane_b32 v255, s0, 49
	s_add_i32 s0, 0, 0x17c00
	v_writelane_b32 v255, s0, 50
	v_writelane_b32 v255, s37, 51
	v_writelane_b32 v255, s60, 52
	s_nop 1
	v_writelane_b32 v255, s61, 53
	s_branch .LBB0_192
